# QKV (EpiRow0) epilogue: hoist 8 rowss loads to top, one wait
# baseline (speedup 1.0000x reference)
; __device__ __forceinline__ float ss_rinv(u64 v) { return __builtin_amdgcn_rsqf((float)v * SS_INV + 1e-6f); }
; __device__ __forceinline__ unsigned cvtpk(float lo, float hi) { f32x2 v = {lo, hi}; bf16x2_t b = __builtin_convertvector(v, bf16x2_t); return __builtin_bit_cast(unsigned, b); }
;     __device__ __forceinline__ void operator()(const f32x4 (&acc)[2][2][4][2], const pg8::Unit& u, int wr, int wc, int fr, int fq) const {
;     ...
;                 const int lrow = u.pm * 256 + ai * 128 + wr * 64 + m * 16 + fr, grow = row_base + lrow;
;                 if (grow >= MREAL) continue;
;                 const float ri = ss_rinv(rowss[grow]);
; #pragma unroll
;                 for (int bj = 0; bj < 2; ++bj) {
;                     const int col0 = u.pn * 256 + bj * 128 + wc * 32 + 8 * fq;
;                     f32x4 v0 = acc[ai][bj][m][0] * ri, v1 = acc[ai][bj][m][1] * ri;
;                     if (MODE == 1) {
; #pragma unroll
;                         for (int i = 0; i < 4; ++i) { const float a = fmaxf(v0[i], 0.f), b = fmaxf(v1[i], 0.f); v0[i] = a * a; v1[i] = b * b; }
;                         u32x4 w; w.x = cvtpk(v0[0], v0[1]); w.y = cvtpk(v0[2], v0[3]); w.z = cvtpk(v1[0], v1[1]); w.w = cvtpk(v1[2], v1[3]);
;                         *(u32x4*)(O + (size_t)lrow * DFF + col0) = w;
;                     } else {
;                         if (col0 < 1280) {
;                             u32x4 w; w.x = cvtpk(v0[0], v0[1]); w.y = cvtpk(v0[2], v0[3]); w.z = cvtpk(v1[0], v1[1]); w.w = cvtpk(v1[2], v1[3]);
;                             *(u32x4*)(O + (size_t)grow * 1280 + col0) = w;
;                         } else {
;                             int s, p, L; row_decode(grow, s, p, L);
;                             const int LS = seq_LS(s);
;                             bf16_t* dst = VT + seq_off_ch(s) / 4 + (size_t)(col0 - 1280) * LS + XPAD + p;
; #pragma unroll
;                             for (int i = 0; i < 4; ++i) { dst[(size_t)i * LS] = (bf16_t)(cvtpk(v0[i], 0.f) & 0xffffu); dst[(size_t)(4 + i) * LS] = (bf16_t)(cvtpk(v1[i], 0.f) & 0xffffu); }
.LBB0_442:
	v_lshl_add_u32 v144, s6, 8, v163
	v_lshl_or_b32 v142, s2, 8, v165
	v_cmp_gt_i32_e32 vcc, s54, v144
	v_ashrrev_i32_e32 v145, 31, v144
	v_lshl_add_u64 v[188:189], v[144:145], 3, s[16:17]
	global_load_dwordx2 v[172:173], v[188:189], off
	global_load_dwordx2 v[174:175], v[188:189], off offset:128
	global_load_dwordx2 v[176:177], v[188:189], off offset:256
	global_load_dwordx2 v[178:179], v[188:189], off offset:384
	global_load_dwordx2 v[180:181], v[188:189], off offset:1024
	global_load_dwordx2 v[182:183], v[188:189], off offset:1152
	global_load_dwordx2 v[184:185], v[188:189], off offset:1280
	global_load_dwordx2 v[186:187], v[188:189], off offset:1408
	s_waitcnt vmcnt(0)
	v_ashrrev_i32_e32 v167, 13, v144
	s_and_saveexec_b64 s[28:29], vcc
	s_cbranch_execz .LBB0_459
	v_mov_b64_e32 v[146:147], v[172:173]
	s_mov_b32 s6, 0x18000
	s_mov_b32 s2, 0x8000
	v_cmp_gt_i32_e64 s[2:3], s2, v144
	v_ffbh_u32_e32 v32, v147
	v_min_u32_e32 v32, 32, v32
	v_lshlrev_b64 v[146:147], v32, v[146:147]
	v_min_u32_e32 v143, 1, v146
	v_or_b32_e32 v143, v147, v143
	v_cvt_f32_u32_e32 v143, v143
	v_sub_u32_e32 v32, 32, v32
	v_ldexp_f32 v32, v143, v32
	v_fmamk_f32 v32, v32, 0x30800000, v203
	v_rsq_f32_e32 v158, v32
	v_subrev_co_u32_e32 v32, vcc, s6, v144
	v_add_u32_e32 v143, 0xffff8000, v144
	s_movk_i32 s6, 0xfcf
	v_lshrrev_b32_e32 v143, 12, v143
	v_and_or_b32 v168, v144, s6, 16
	s_movk_i32 s6, 0x1fcf
	v_lshrrev_b32_e32 v32, 4, v32
	v_add_u32_e32 v143, 4, v143
	v_and_or_b32 v169, v144, s6, 16
	s_movk_i32 s6, 0x4ff
	v_pk_mul_f32 v[128:129], v[128:129], v[158:159] op_sel_hi:[1,0]
	v_pk_mul_f32 v[126:127], v[126:127], v[158:159] op_sel_hi:[1,0]
	v_pk_mul_f32 v[124:125], v[124:125], v[158:159] op_sel_hi:[1,0]
	v_pk_mul_f32 v[122:123], v[122:123], v[158:159] op_sel_hi:[1,0]
	v_cmp_lt_i32_e64 s[6:7], s6, v142
	v_cndmask_b32_e32 v170, v32, v143, vcc
	s_and_saveexec_b64 s[8:9], s[6:7]
	s_xor_b64 s[30:31], exec, s[8:9]
	s_cbranch_execz .LBB0_449
	v_cndmask_b32_e64 v32, v170, v167, s[2:3]
	v_cmp_gt_i32_e64 s[6:7], 4, v32
	v_cmp_lt_i32_e64 s[8:9], 3, v32
	s_and_saveexec_b64 s[50:51], s[8:9]
	s_xor_b64 s[8:9], exec, s[50:51]
	v_add_u32_e32 v32, -4, v32
	s_mov_b32 s21, 0x410000
	v_mov_b64_e32 v[146:147], 0x2040000
	v_mad_u64_u32 v[160:161], s[50:51], v32, s21, v[146:147]
	s_andn2_saveexec_b64 s[8:9], s[8:9]
	s_mov_b32 s21, 0x810000
	v_mad_i64_i32 v[160:161], s[50:51], v32, s21, 0
	s_or_b64 exec, exec, s[8:9]
	v_mov_b32_e32 v143, 0x1040
	v_mov_b32_e32 v146, 0x2040
	v_cndmask_b32_e64 v143, v143, v146, s[6:7]
	v_lshrrev_b64 v[146:147], 1, v[160:161]
	v_cndmask_b32_e32 v32, v162, v168, vcc
	v_and_b32_e32 v146, -2, v146
	v_add_u32_e32 v148, 0xfffffb00, v142
	v_cndmask_b32_e64 v32, v32, v169, s[2:3]
	v_lshl_add_u64 v[146:147], s[14:15], 0, v[146:147]
	v_mad_u64_u32 v[148:149], s[6:7], v143, v148, 0
	v_lshl_add_u64 v[146:147], v[148:149], 1, v[146:147]
	v_lshlrev_b32_e32 v32, 1, v32
	v_lshl_add_u64 v[146:147], v[146:147], 0, v[32:33]
	v_lshlrev_b32_e32 v148, 3, v143
	v_mov_b32_e32 v149, v33
	v_cvt_pk_bf16_f32 v122, v122, s0
	v_lshl_add_u64 v[148:149], v[146:147], 0, v[148:149]
	v_cvt_pk_bf16_f32 v32, v126, s0
	global_store_short v[148:149], v122, off offset:96
	v_cvt_pk_bf16_f32 v122, v127, s0
	v_lshlrev_b32_e32 v126, 1, v143
	v_mov_b32_e32 v127, v33
	v_lshl_add_u64 v[126:127], v[146:147], 0, v[126:127]
	global_store_short v[126:127], v122, off offset:96
	v_mul_u32_u24_e32 v122, 5, v143
	v_cvt_pk_bf16_f32 v126, v123, s0
	v_lshlrev_b32_e32 v122, 1, v122
	v_mov_b32_e32 v123, v33
	global_store_short v[146:147], v32, off offset:96
	v_lshlrev_b32_e32 v32, 2, v143
	v_lshl_add_u64 v[122:123], v[146:147], 0, v[122:123]
	global_store_short v[122:123], v126, off offset:96
	v_lshl_add_u64 v[122:123], v[146:147], 0, v[32:33]
	v_mul_u32_u24_e32 v32, 6, v143
	v_cvt_pk_bf16_f32 v126, v128, s0
	v_lshlrev_b32_e32 v32, 1, v32
	global_store_short v[122:123], v126, off offset:96
	v_lshl_add_u64 v[122:123], v[146:147], 0, v[32:33]
	v_mul_u32_u24_e32 v32, 3, v143
	v_cvt_pk_bf16_f32 v124, v124, s0
	v_lshlrev_b32_e32 v32, 1, v32
	global_store_short v[122:123], v124, off offset:96
	v_lshl_add_u64 v[122:123], v[146:147], 0, v[32:33]
	v_mul_u32_u24_e32 v32, 7, v143
	v_cvt_pk_bf16_f32 v124, v129, s0
	v_lshlrev_b32_e32 v32, 1, v32
	global_store_short v[122:123], v124, off offset:96
	v_cvt_pk_bf16_f32 v124, v125, s0
	v_lshl_add_u64 v[122:123], v[146:147], 0, v[32:33]
	global_store_short v[122:123], v124, off offset:96

; __device__ __forceinline__ float ss_rinv(u64 v) { return __builtin_amdgcn_rsqf((float)v * SS_INV + 1e-6f); }
; __device__ __forceinline__ unsigned cvtpk(float lo, float hi) { f32x2 v = {lo, hi}; bf16x2_t b = __builtin_convertvector(v, bf16x2_t); return __builtin_bit_cast(unsigned, b); }
;     __device__ __forceinline__ void operator()(const f32x4 (&acc)[2][2][4][2], const pg8::Unit& u, int wr, int wc, int fr, int fq) const {
;     ...
;                 const int lrow = u.pm * 256 + ai * 128 + wr * 64 + m * 16 + fr, grow = row_base + lrow;
;                 if (grow >= MREAL) continue;
;                 const float ri = ss_rinv(rowss[grow]);
; #pragma unroll
;                 for (int bj = 0; bj < 2; ++bj) {
;                     const int col0 = u.pn * 256 + bj * 128 + wc * 32 + 8 * fq;
;                     f32x4 v0 = acc[ai][bj][m][0] * ri, v1 = acc[ai][bj][m][1] * ri;
;                     if (MODE == 1) {
; #pragma unroll
;                         for (int i = 0; i < 4; ++i) { const float a = fmaxf(v0[i], 0.f), b = fmaxf(v1[i], 0.f); v0[i] = a * a; v1[i] = b * b; }
;                         u32x4 w; w.x = cvtpk(v0[0], v0[1]); w.y = cvtpk(v0[2], v0[3]); w.z = cvtpk(v1[0], v1[1]); w.w = cvtpk(v1[2], v1[3]);
;                         *(u32x4*)(O + (size_t)lrow * DFF + col0) = w;
;                     } else {
;                         if (col0 < 1280) {
;                             u32x4 w; w.x = cvtpk(v0[0], v0[1]); w.y = cvtpk(v0[2], v0[3]); w.z = cvtpk(v1[0], v1[1]); w.w = cvtpk(v1[2], v1[3]);
;                             *(u32x4*)(O + (size_t)grow * 1280 + col0) = w;
;                         } else {
;                             int s, p, L; row_decode(grow, s, p, L);
;                             const int LS = seq_LS(s);
;                             bf16_t* dst = VT + seq_off_ch(s) / 4 + (size_t)(col0 - 1280) * LS + XPAD + p;
; #pragma unroll
;                             for (int i = 0; i < 4; ++i) { dst[(size_t)i * LS] = (bf16_t)(cvtpk(v0[i], 0.f) & 0xffffu); dst[(size_t)(4 + i) * LS] = (bf16_t)(cvtpk(v1[i], 0.f) & 0xffffu); }
.LBB0_459:
	s_or_b64 exec, exec, s[28:29]
	v_or_b32_e32 v115, 16, v144
	v_cmp_gt_i32_e32 vcc, s54, v115
	s_and_saveexec_b64 s[28:29], vcc
	s_cbranch_execz .LBB0_476
	v_mov_b64_e32 v[116:117], v[174:175]
	s_mov_b32 s2, 0x8000
	v_cmp_gt_i32_e32 vcc, s2, v115
	s_mov_b32 s2, 0x18000
	v_cmp_gt_u32_e64 s[2:3], s2, v144
	s_movk_i32 s6, 0x4ff
	v_cmp_lt_i32_e64 s[6:7], s6, v142
	v_ffbh_u32_e32 v32, v117
	v_min_u32_e32 v32, 32, v32
	v_lshlrev_b64 v[116:117], v32, v[116:117]
	v_min_u32_e32 v114, 1, v116
	v_or_b32_e32 v114, v117, v114
	v_cvt_f32_u32_e32 v114, v114
	v_sub_u32_e32 v32, 32, v32
	v_add_u32_e32 v116, 0xffff8010, v144
	v_lshrrev_b32_e32 v116, 12, v116
	v_ldexp_f32 v32, v114, v32
	v_fmamk_f32 v32, v32, 0x30800000, v203
	v_rsq_f32_e32 v114, v32
	v_add_u32_e32 v32, 0xfffe8010, v144
	v_and_b32_e32 v117, 0xfdf, v115
	v_lshrrev_b32_e32 v32, 4, v32
	v_add_u32_e32 v116, 4, v116
	v_add_u32_e32 v118, 16, v117
	v_and_b32_e32 v117, 0x1fdf, v115
	v_add_u32_e32 v119, 16, v117
	v_pk_mul_f32 v[112:113], v[112:113], v[114:115] op_sel_hi:[1,0]
	v_pk_mul_f32 v[110:111], v[110:111], v[114:115] op_sel_hi:[1,0]
	v_pk_mul_f32 v[108:109], v[108:109], v[114:115] op_sel_hi:[1,0]
	v_pk_mul_f32 v[106:107], v[106:107], v[114:115] op_sel_hi:[1,0]
	v_cndmask_b32_e64 v120, v32, v116, s[2:3]
	s_and_saveexec_b64 s[8:9], s[6:7]
	s_xor_b64 s[30:31], exec, s[8:9]
	s_cbranch_execz .LBB0_466
	v_cndmask_b32_e32 v32, v120, v167, vcc
	v_cmp_gt_i32_e64 s[6:7], 4, v32
	v_cmp_lt_i32_e64 s[8:9], 3, v32
	s_and_saveexec_b64 s[50:51], s[8:9]
	s_xor_b64 s[8:9], exec, s[50:51]
	v_add_u32_e32 v32, -4, v32
	s_mov_b32 s21, 0x410000
	v_mov_b64_e32 v[116:117], 0x2040000
	v_mad_u64_u32 v[116:117], s[50:51], v32, s21, v[116:117]
	s_andn2_saveexec_b64 s[8:9], s[8:9]
	s_mov_b32 s21, 0x810000
	v_mad_i64_i32 v[116:117], s[50:51], v32, s21, 0
	s_or_b64 exec, exec, s[8:9]
	v_mov_b32_e32 v121, 0x1040
	v_mov_b32_e32 v122, 0x2040
	v_lshrrev_b64 v[116:117], 1, v[116:117]
	v_cndmask_b32_e64 v32, v162, v118, s[2:3]
	v_cndmask_b32_e64 v121, v121, v122, s[6:7]
	v_and_b32_e32 v116, -2, v116
	v_add_u32_e32 v122, 0xfffffb00, v142
	v_cndmask_b32_e32 v32, v32, v119, vcc
	v_lshl_add_u64 v[116:117], s[14:15], 0, v[116:117]
	v_mad_u64_u32 v[122:123], s[6:7], v121, v122, 0
	v_lshl_add_u64 v[116:117], v[122:123], 1, v[116:117]
	v_lshlrev_b32_e32 v32, 1, v32
	v_lshl_add_u64 v[116:117], v[116:117], 0, v[32:33]
	v_lshlrev_b32_e32 v122, 3, v121
	v_mov_b32_e32 v123, v33
	v_cvt_pk_bf16_f32 v106, v106, s0
	v_lshl_add_u64 v[122:123], v[116:117], 0, v[122:123]
	v_cvt_pk_bf16_f32 v32, v110, s0
	global_store_short v[122:123], v106, off offset:96
	v_cvt_pk_bf16_f32 v106, v111, s0
	v_lshlrev_b32_e32 v110, 1, v121
	v_mov_b32_e32 v111, v33
	v_lshl_add_u64 v[110:111], v[116:117], 0, v[110:111]
	global_store_short v[110:111], v106, off offset:96
	v_mul_u32_u24_e32 v106, 5, v121
	v_cvt_pk_bf16_f32 v110, v107, s0
	v_lshlrev_b32_e32 v106, 1, v106
	v_mov_b32_e32 v107, v33
	global_store_short v[116:117], v32, off offset:96
	v_lshlrev_b32_e32 v32, 2, v121
	v_lshl_add_u64 v[106:107], v[116:117], 0, v[106:107]
	global_store_short v[106:107], v110, off offset:96
	v_lshl_add_u64 v[106:107], v[116:117], 0, v[32:33]
	v_mul_u32_u24_e32 v32, 6, v121
	v_cvt_pk_bf16_f32 v110, v112, s0
	v_lshlrev_b32_e32 v32, 1, v32
	global_store_short v[106:107], v110, off offset:96
	v_lshl_add_u64 v[106:107], v[116:117], 0, v[32:33]
	v_mul_u32_u24_e32 v32, 3, v121
	v_cvt_pk_bf16_f32 v108, v108, s0
	v_lshlrev_b32_e32 v32, 1, v32
	global_store_short v[106:107], v108, off offset:96
	v_lshl_add_u64 v[106:107], v[116:117], 0, v[32:33]
	v_mul_u32_u24_e32 v32, 7, v121
	v_cvt_pk_bf16_f32 v108, v113, s0
	v_lshlrev_b32_e32 v32, 1, v32
	global_store_short v[106:107], v108, off offset:96
	v_cvt_pk_bf16_f32 v108, v109, s0
	v_lshl_add_u64 v[106:107], v[116:117], 0, v[32:33]
	global_store_short v[106:107], v108, off offset:96

; __device__ __forceinline__ float ss_rinv(u64 v) { return __builtin_amdgcn_rsqf((float)v * SS_INV + 1e-6f); }
; __device__ __forceinline__ unsigned cvtpk(float lo, float hi) { f32x2 v = {lo, hi}; bf16x2_t b = __builtin_convertvector(v, bf16x2_t); return __builtin_bit_cast(unsigned, b); }
;     __device__ __forceinline__ void operator()(const f32x4 (&acc)[2][2][4][2], const pg8::Unit& u, int wr, int wc, int fr, int fq) const {
;     ...
;                 const int lrow = u.pm * 256 + ai * 128 + wr * 64 + m * 16 + fr, grow = row_base + lrow;
;                 if (grow >= MREAL) continue;
;                 const float ri = ss_rinv(rowss[grow]);
; #pragma unroll
;                 for (int bj = 0; bj < 2; ++bj) {
;                     const int col0 = u.pn * 256 + bj * 128 + wc * 32 + 8 * fq;
;                     f32x4 v0 = acc[ai][bj][m][0] * ri, v1 = acc[ai][bj][m][1] * ri;
;                     if (MODE == 1) {
; #pragma unroll
;                         for (int i = 0; i < 4; ++i) { const float a = fmaxf(v0[i], 0.f), b = fmaxf(v1[i], 0.f); v0[i] = a * a; v1[i] = b * b; }
;                         u32x4 w; w.x = cvtpk(v0[0], v0[1]); w.y = cvtpk(v0[2], v0[3]); w.z = cvtpk(v1[0], v1[1]); w.w = cvtpk(v1[2], v1[3]);
;                         *(u32x4*)(O + (size_t)lrow * DFF + col0) = w;
;                     } else {
;                         if (col0 < 1280) {
;                             u32x4 w; w.x = cvtpk(v0[0], v0[1]); w.y = cvtpk(v0[2], v0[3]); w.z = cvtpk(v1[0], v1[1]); w.w = cvtpk(v1[2], v1[3]);
;                             *(u32x4*)(O + (size_t)grow * 1280 + col0) = w;
;                         } else {
;                             int s, p, L; row_decode(grow, s, p, L);
;                             const int LS = seq_LS(s);
;                             bf16_t* dst = VT + seq_off_ch(s) / 4 + (size_t)(col0 - 1280) * LS + XPAD + p;
; #pragma unroll
;                             for (int i = 0; i < 4; ++i) { dst[(size_t)i * LS] = (bf16_t)(cvtpk(v0[i], 0.f) & 0xffffu); dst[(size_t)(4 + i) * LS] = (bf16_t)(cvtpk(v1[i], 0.f) & 0xffffu); }
.LBB0_476:
	s_or_b64 exec, exec, s[28:29]
	v_or_b32_e32 v99, 32, v144
	v_cmp_gt_i32_e32 vcc, s54, v99
	s_and_saveexec_b64 s[28:29], vcc
	s_cbranch_execz .LBB0_493
	v_mov_b64_e32 v[100:101], v[176:177]
	s_mov_b32 s2, 0x8000
	s_movk_i32 s6, 0xfef
	v_cmp_gt_i32_e32 vcc, s2, v99
	s_mov_b32 s2, 0x18000
	v_and_or_b32 v102, v99, s6, 16
	s_movk_i32 s6, 0x1fef
	v_cmp_gt_u32_e64 s[2:3], s2, v144
	v_and_or_b32 v103, v99, s6, 16
	s_movk_i32 s6, 0x4ff
	v_cmp_lt_i32_e64 s[6:7], s6, v142
	v_ffbh_u32_e32 v32, v101
	v_min_u32_e32 v32, 32, v32
	v_lshlrev_b64 v[100:101], v32, v[100:101]
	v_min_u32_e32 v98, 1, v100
	v_or_b32_e32 v98, v101, v98
	v_cvt_f32_u32_e32 v98, v98
	v_sub_u32_e32 v32, 32, v32
	v_add_u32_e32 v100, 0xffff8020, v144
	v_lshrrev_b32_e32 v100, 12, v100
	v_ldexp_f32 v32, v98, v32
	v_fmamk_f32 v32, v32, 0x30800000, v203
	v_rsq_f32_e32 v98, v32
	v_add_u32_e32 v32, 0xfffe8020, v144
	v_lshrrev_b32_e32 v32, 4, v32
	v_add_u32_e32 v100, 4, v100
	v_pk_mul_f32 v[96:97], v[96:97], v[98:99] op_sel_hi:[1,0]
	v_pk_mul_f32 v[94:95], v[94:95], v[98:99] op_sel_hi:[1,0]
	v_pk_mul_f32 v[92:93], v[92:93], v[98:99] op_sel_hi:[1,0]
	v_pk_mul_f32 v[90:91], v[90:91], v[98:99] op_sel_hi:[1,0]
	v_cndmask_b32_e64 v104, v32, v100, s[2:3]
	s_and_saveexec_b64 s[8:9], s[6:7]
	s_xor_b64 s[30:31], exec, s[8:9]
	s_cbranch_execz .LBB0_483
	v_cndmask_b32_e32 v32, v104, v167, vcc
	v_cmp_gt_i32_e64 s[6:7], 4, v32
	v_cmp_lt_i32_e64 s[8:9], 3, v32
	s_and_saveexec_b64 s[50:51], s[8:9]
	s_xor_b64 s[8:9], exec, s[50:51]
	v_add_u32_e32 v32, -4, v32
	s_mov_b32 s21, 0x410000
	v_mov_b64_e32 v[100:101], 0x2040000
	v_mad_u64_u32 v[100:101], s[50:51], v32, s21, v[100:101]
	s_andn2_saveexec_b64 s[8:9], s[8:9]
	s_mov_b32 s21, 0x810000
	v_mad_i64_i32 v[100:101], s[50:51], v32, s21, 0
	s_or_b64 exec, exec, s[8:9]
	v_mov_b32_e32 v105, 0x1040
	v_mov_b32_e32 v106, 0x2040
	v_lshrrev_b64 v[100:101], 1, v[100:101]
	v_cndmask_b32_e64 v32, v162, v102, s[2:3]
	v_cndmask_b32_e64 v105, v105, v106, s[6:7]
	v_and_b32_e32 v100, -2, v100
	v_add_u32_e32 v106, 0xfffffb00, v142
	v_cndmask_b32_e32 v32, v32, v103, vcc
	v_lshl_add_u64 v[100:101], s[14:15], 0, v[100:101]
	v_mad_u64_u32 v[106:107], s[6:7], v105, v106, 0
	v_lshl_add_u64 v[100:101], v[106:107], 1, v[100:101]
	v_lshlrev_b32_e32 v32, 1, v32
	v_lshl_add_u64 v[100:101], v[100:101], 0, v[32:33]
	v_lshlrev_b32_e32 v106, 3, v105
	v_mov_b32_e32 v107, v33
	v_cvt_pk_bf16_f32 v90, v90, s0
	v_lshl_add_u64 v[106:107], v[100:101], 0, v[106:107]
	v_cvt_pk_bf16_f32 v32, v94, s0
	global_store_short v[106:107], v90, off offset:96
	v_cvt_pk_bf16_f32 v90, v95, s0
	v_lshlrev_b32_e32 v94, 1, v105
	v_mov_b32_e32 v95, v33
	v_lshl_add_u64 v[94:95], v[100:101], 0, v[94:95]
	global_store_short v[94:95], v90, off offset:96
	v_mul_u32_u24_e32 v90, 5, v105
	v_cvt_pk_bf16_f32 v94, v91, s0
	v_lshlrev_b32_e32 v90, 1, v90
	v_mov_b32_e32 v91, v33
	global_store_short v[100:101], v32, off offset:96
	v_lshlrev_b32_e32 v32, 2, v105
	v_lshl_add_u64 v[90:91], v[100:101], 0, v[90:91]
	global_store_short v[90:91], v94, off offset:96
	v_lshl_add_u64 v[90:91], v[100:101], 0, v[32:33]
	v_mul_u32_u24_e32 v32, 6, v105
	v_cvt_pk_bf16_f32 v94, v96, s0
	v_lshlrev_b32_e32 v32, 1, v32
	global_store_short v[90:91], v94, off offset:96
	v_lshl_add_u64 v[90:91], v[100:101], 0, v[32:33]
	v_mul_u32_u24_e32 v32, 3, v105
	v_cvt_pk_bf16_f32 v92, v92, s0
	v_lshlrev_b32_e32 v32, 1, v32
	global_store_short v[90:91], v92, off offset:96
	v_lshl_add_u64 v[90:91], v[100:101], 0, v[32:33]
	v_mul_u32_u24_e32 v32, 7, v105
	v_cvt_pk_bf16_f32 v92, v97, s0
	v_lshlrev_b32_e32 v32, 1, v32
	global_store_short v[90:91], v92, off offset:96
	v_cvt_pk_bf16_f32 v92, v93, s0
	v_lshl_add_u64 v[90:91], v[100:101], 0, v[32:33]
	global_store_short v[90:91], v92, off offset:96

; __device__ __forceinline__ float ss_rinv(u64 v) { return __builtin_amdgcn_rsqf((float)v * SS_INV + 1e-6f); }
; __device__ __forceinline__ unsigned cvtpk(float lo, float hi) { f32x2 v = {lo, hi}; bf16x2_t b = __builtin_convertvector(v, bf16x2_t); return __builtin_bit_cast(unsigned, b); }
;     __device__ __forceinline__ void operator()(const f32x4 (&acc)[2][2][4][2], const pg8::Unit& u, int wr, int wc, int fr, int fq) const {
;     ...
;                 const int lrow = u.pm * 256 + ai * 128 + wr * 64 + m * 16 + fr, grow = row_base + lrow;
;                 if (grow >= MREAL) continue;
;                 const float ri = ss_rinv(rowss[grow]);
; #pragma unroll
;                 for (int bj = 0; bj < 2; ++bj) {
;                     const int col0 = u.pn * 256 + bj * 128 + wc * 32 + 8 * fq;
;                     f32x4 v0 = acc[ai][bj][m][0] * ri, v1 = acc[ai][bj][m][1] * ri;
;                     if (MODE == 1) {
; #pragma unroll
;                         for (int i = 0; i < 4; ++i) { const float a = fmaxf(v0[i], 0.f), b = fmaxf(v1[i], 0.f); v0[i] = a * a; v1[i] = b * b; }
;                         u32x4 w; w.x = cvtpk(v0[0], v0[1]); w.y = cvtpk(v0[2], v0[3]); w.z = cvtpk(v1[0], v1[1]); w.w = cvtpk(v1[2], v1[3]);
;                         *(u32x4*)(O + (size_t)lrow * DFF + col0) = w;
;                     } else {
;                         if (col0 < 1280) {
;                             u32x4 w; w.x = cvtpk(v0[0], v0[1]); w.y = cvtpk(v0[2], v0[3]); w.z = cvtpk(v1[0], v1[1]); w.w = cvtpk(v1[2], v1[3]);
;                             *(u32x4*)(O + (size_t)grow * 1280 + col0) = w;
;                         } else {
;                             int s, p, L; row_decode(grow, s, p, L);
;                             const int LS = seq_LS(s);
;                             bf16_t* dst = VT + seq_off_ch(s) / 4 + (size_t)(col0 - 1280) * LS + XPAD + p;
; #pragma unroll
;                             for (int i = 0; i < 4; ++i) { dst[(size_t)i * LS] = (bf16_t)(cvtpk(v0[i], 0.f) & 0xffffu); dst[(size_t)(4 + i) * LS] = (bf16_t)(cvtpk(v1[i], 0.f) & 0xffffu); }
.LBB0_493:
	s_or_b64 exec, exec, s[28:29]
	v_or_b32_e32 v83, 48, v144
	v_cmp_gt_i32_e32 vcc, s54, v83
	s_and_saveexec_b64 s[28:29], vcc
	s_cbranch_execz .LBB0_510
	v_mov_b64_e32 v[84:85], v[178:179]
	s_mov_b32 s2, 0x8000
	v_cmp_gt_i32_e32 vcc, s2, v83
	s_mov_b32 s2, 0x18000
	v_cmp_gt_u32_e64 s[2:3], s2, v144
	s_movk_i32 s6, 0x4ff
	v_cmp_lt_i32_e64 s[6:7], s6, v142
	v_ffbh_u32_e32 v32, v85
	v_min_u32_e32 v32, 32, v32
	v_lshlrev_b64 v[84:85], v32, v[84:85]
	v_min_u32_e32 v82, 1, v84
	v_or_b32_e32 v82, v85, v82
	v_cvt_f32_u32_e32 v82, v82
	v_sub_u32_e32 v32, 32, v32
	v_add_u32_e32 v84, 0xffff8030, v144
	v_lshrrev_b32_e32 v84, 12, v84
	v_ldexp_f32 v32, v82, v32
	v_fmamk_f32 v32, v32, 0x30800000, v203
	v_rsq_f32_e32 v82, v32
	v_add_u32_e32 v32, 0xfffe8030, v144
	v_and_b32_e32 v85, 0xfff, v83
	v_lshrrev_b32_e32 v32, 4, v32
	v_add_u32_e32 v84, 4, v84
	v_add_u32_e32 v86, 16, v85
	v_and_b32_e32 v85, 0x1fff, v83
	v_add_u32_e32 v87, 16, v85
	v_pk_mul_f32 v[80:81], v[80:81], v[82:83] op_sel_hi:[1,0]
	v_pk_mul_f32 v[78:79], v[78:79], v[82:83] op_sel_hi:[1,0]
	v_pk_mul_f32 v[76:77], v[76:77], v[82:83] op_sel_hi:[1,0]
	v_pk_mul_f32 v[74:75], v[74:75], v[82:83] op_sel_hi:[1,0]
	v_cndmask_b32_e64 v88, v32, v84, s[2:3]
	s_and_saveexec_b64 s[8:9], s[6:7]
	s_xor_b64 s[30:31], exec, s[8:9]
	s_cbranch_execz .LBB0_500
	v_cndmask_b32_e32 v32, v88, v167, vcc
	v_cmp_gt_i32_e64 s[6:7], 4, v32
	v_cmp_lt_i32_e64 s[8:9], 3, v32
	s_and_saveexec_b64 s[50:51], s[8:9]
	s_xor_b64 s[8:9], exec, s[50:51]
	v_add_u32_e32 v32, -4, v32
	s_mov_b32 s21, 0x410000
	v_mov_b64_e32 v[84:85], 0x2040000
	v_mad_u64_u32 v[84:85], s[50:51], v32, s21, v[84:85]
	s_andn2_saveexec_b64 s[8:9], s[8:9]
	s_mov_b32 s21, 0x810000
	v_mad_i64_i32 v[84:85], s[50:51], v32, s21, 0
	s_or_b64 exec, exec, s[8:9]
	v_mov_b32_e32 v89, 0x1040
	v_mov_b32_e32 v90, 0x2040
	v_lshrrev_b64 v[84:85], 1, v[84:85]
	v_cndmask_b32_e64 v32, v162, v86, s[2:3]
	v_cndmask_b32_e64 v89, v89, v90, s[6:7]
	v_and_b32_e32 v84, -2, v84
	v_add_u32_e32 v90, 0xfffffb00, v142
	v_cndmask_b32_e32 v32, v32, v87, vcc
	v_lshl_add_u64 v[84:85], s[14:15], 0, v[84:85]
	v_mad_u64_u32 v[90:91], s[6:7], v89, v90, 0
	v_lshl_add_u64 v[84:85], v[90:91], 1, v[84:85]
	v_lshlrev_b32_e32 v32, 1, v32
	v_lshl_add_u64 v[84:85], v[84:85], 0, v[32:33]
	v_lshlrev_b32_e32 v90, 3, v89
	v_mov_b32_e32 v91, v33
	v_cvt_pk_bf16_f32 v74, v74, s0
	v_lshl_add_u64 v[90:91], v[84:85], 0, v[90:91]
	v_cvt_pk_bf16_f32 v32, v78, s0
	global_store_short v[90:91], v74, off offset:96
	v_cvt_pk_bf16_f32 v74, v79, s0
	v_lshlrev_b32_e32 v78, 1, v89
	v_mov_b32_e32 v79, v33
	v_lshl_add_u64 v[78:79], v[84:85], 0, v[78:79]
	global_store_short v[78:79], v74, off offset:96
	v_mul_u32_u24_e32 v74, 5, v89
	v_cvt_pk_bf16_f32 v78, v75, s0
	v_lshlrev_b32_e32 v74, 1, v74
	v_mov_b32_e32 v75, v33
	global_store_short v[84:85], v32, off offset:96
	v_lshlrev_b32_e32 v32, 2, v89
	v_lshl_add_u64 v[74:75], v[84:85], 0, v[74:75]
	global_store_short v[74:75], v78, off offset:96
	v_lshl_add_u64 v[74:75], v[84:85], 0, v[32:33]
	v_mul_u32_u24_e32 v32, 6, v89
	v_cvt_pk_bf16_f32 v78, v80, s0
	v_lshlrev_b32_e32 v32, 1, v32
	global_store_short v[74:75], v78, off offset:96
	v_lshl_add_u64 v[74:75], v[84:85], 0, v[32:33]
	v_mul_u32_u24_e32 v32, 3, v89
	v_cvt_pk_bf16_f32 v76, v76, s0
	v_lshlrev_b32_e32 v32, 1, v32
	global_store_short v[74:75], v76, off offset:96
	v_lshl_add_u64 v[74:75], v[84:85], 0, v[32:33]
	v_mul_u32_u24_e32 v32, 7, v89
	v_cvt_pk_bf16_f32 v76, v81, s0
	v_lshlrev_b32_e32 v32, 1, v32
	global_store_short v[74:75], v76, off offset:96
	v_cvt_pk_bf16_f32 v76, v77, s0
	v_lshl_add_u64 v[74:75], v[84:85], 0, v[32:33]
	global_store_short v[74:75], v76, off offset:96

; __device__ __forceinline__ float ss_rinv(u64 v) { return __builtin_amdgcn_rsqf((float)v * SS_INV + 1e-6f); }
; __device__ __forceinline__ unsigned cvtpk(float lo, float hi) { f32x2 v = {lo, hi}; bf16x2_t b = __builtin_convertvector(v, bf16x2_t); return __builtin_bit_cast(unsigned, b); }
;     __device__ __forceinline__ void operator()(const f32x4 (&acc)[2][2][4][2], const pg8::Unit& u, int wr, int wc, int fr, int fq) const {
;     ...
;                 const int lrow = u.pm * 256 + ai * 128 + wr * 64 + m * 16 + fr, grow = row_base + lrow;
;                 if (grow >= MREAL) continue;
;                 const float ri = ss_rinv(rowss[grow]);
; #pragma unroll
;                 for (int bj = 0; bj < 2; ++bj) {
;                     const int col0 = u.pn * 256 + bj * 128 + wc * 32 + 8 * fq;
;                     f32x4 v0 = acc[ai][bj][m][0] * ri, v1 = acc[ai][bj][m][1] * ri;
;                     if (MODE == 1) {
; #pragma unroll
;                         for (int i = 0; i < 4; ++i) { const float a = fmaxf(v0[i], 0.f), b = fmaxf(v1[i], 0.f); v0[i] = a * a; v1[i] = b * b; }
;                         u32x4 w; w.x = cvtpk(v0[0], v0[1]); w.y = cvtpk(v0[2], v0[3]); w.z = cvtpk(v1[0], v1[1]); w.w = cvtpk(v1[2], v1[3]);
;                         *(u32x4*)(O + (size_t)lrow * DFF + col0) = w;
;                     } else {
;                         if (col0 < 1280) {
;                             u32x4 w; w.x = cvtpk(v0[0], v0[1]); w.y = cvtpk(v0[2], v0[3]); w.z = cvtpk(v1[0], v1[1]); w.w = cvtpk(v1[2], v1[3]);
;                             *(u32x4*)(O + (size_t)grow * 1280 + col0) = w;
;                         } else {
;                             int s, p, L; row_decode(grow, s, p, L);
;                             const int LS = seq_LS(s);
;                             bf16_t* dst = VT + seq_off_ch(s) / 4 + (size_t)(col0 - 1280) * LS + XPAD + p;
; #pragma unroll
;                             for (int i = 0; i < 4; ++i) { dst[(size_t)i * LS] = (bf16_t)(cvtpk(v0[i], 0.f) & 0xffffu); dst[(size_t)(4 + i) * LS] = (bf16_t)(cvtpk(v1[i], 0.f) & 0xffffu); }
.LBB0_510:
	s_or_b64 exec, exec, s[28:29]
	v_add_u32_e32 v67, 0x80, v144
	v_cmp_gt_i32_e32 vcc, s54, v67
	s_and_saveexec_b64 s[28:29], vcc
	s_cbranch_execz .LBB0_527
	v_mov_b64_e32 v[68:69], v[180:181]
	s_mov_b32 s2, 0x8000
	s_movk_i32 s6, 0xfcf
	v_cmp_gt_i32_e32 vcc, s2, v67
	s_mov_b32 s2, 0x18000
	v_and_or_b32 v70, v67, s6, 16
	s_movk_i32 s6, 0x1fcf
	v_cmp_gt_u32_e64 s[2:3], s2, v67
	v_and_or_b32 v71, v67, s6, 16
	s_movk_i32 s6, 0x4ff
	v_ashrrev_i32_e32 v72, 13, v67
	v_cmp_lt_i32_e64 s[6:7], s6, v142
	v_ffbh_u32_e32 v32, v69
	v_min_u32_e32 v32, 32, v32
	v_lshlrev_b64 v[68:69], v32, v[68:69]
	v_min_u32_e32 v66, 1, v68
	v_or_b32_e32 v66, v69, v66
	v_cvt_f32_u32_e32 v66, v66
	v_sub_u32_e32 v32, 32, v32
	v_add_u32_e32 v68, 0xffff8080, v144
	v_lshrrev_b32_e32 v68, 12, v68
	v_ldexp_f32 v32, v66, v32
	v_fmamk_f32 v32, v32, 0x30800000, v203
	v_rsq_f32_e32 v66, v32
	v_add_u32_e32 v32, 0xfffe8080, v144
	v_lshrrev_b32_e32 v32, 4, v32
	v_add_u32_e32 v68, 4, v68
	v_pk_mul_f32 v[64:65], v[64:65], v[66:67] op_sel_hi:[1,0]
	v_pk_mul_f32 v[62:63], v[62:63], v[66:67] op_sel_hi:[1,0]
	v_pk_mul_f32 v[60:61], v[60:61], v[66:67] op_sel_hi:[1,0]
	v_pk_mul_f32 v[58:59], v[58:59], v[66:67] op_sel_hi:[1,0]
	v_cndmask_b32_e64 v73, v32, v68, s[2:3]
	s_and_saveexec_b64 s[8:9], s[6:7]
	s_xor_b64 s[30:31], exec, s[8:9]
	s_cbranch_execz .LBB0_517
	v_cndmask_b32_e32 v32, v73, v72, vcc
	v_cmp_gt_i32_e64 s[6:7], 4, v32
	v_cmp_lt_i32_e64 s[8:9], 3, v32
	s_and_saveexec_b64 s[50:51], s[8:9]
	s_xor_b64 s[8:9], exec, s[50:51]
	v_add_u32_e32 v32, -4, v32
	s_mov_b32 s21, 0x410000
	v_mov_b64_e32 v[68:69], 0x2040000
	v_mad_u64_u32 v[68:69], s[50:51], v32, s21, v[68:69]
	s_andn2_saveexec_b64 s[8:9], s[8:9]
	s_mov_b32 s21, 0x810000
	v_mad_i64_i32 v[68:69], s[50:51], v32, s21, 0
	s_or_b64 exec, exec, s[8:9]
	v_mov_b32_e32 v74, 0x1040
	v_mov_b32_e32 v75, 0x2040
	v_lshrrev_b64 v[68:69], 1, v[68:69]
	v_cndmask_b32_e64 v32, v162, v70, s[2:3]
	v_cndmask_b32_e64 v76, v74, v75, s[6:7]
	v_and_b32_e32 v68, -2, v68
	v_add_u32_e32 v74, 0xfffffb00, v142
	v_cndmask_b32_e32 v32, v32, v71, vcc
	v_lshl_add_u64 v[68:69], s[14:15], 0, v[68:69]
	v_mad_u64_u32 v[74:75], s[6:7], v76, v74, 0
	v_lshl_add_u64 v[68:69], v[74:75], 1, v[68:69]
	v_lshlrev_b32_e32 v32, 1, v32
	v_lshl_add_u64 v[68:69], v[68:69], 0, v[32:33]
	v_lshlrev_b32_e32 v74, 3, v76
	v_mov_b32_e32 v75, v33
	v_cvt_pk_bf16_f32 v58, v58, s0
	v_lshl_add_u64 v[74:75], v[68:69], 0, v[74:75]
	v_cvt_pk_bf16_f32 v32, v62, s0
	global_store_short v[74:75], v58, off offset:96
	v_cvt_pk_bf16_f32 v58, v63, s0
	v_lshlrev_b32_e32 v62, 1, v76
	v_mov_b32_e32 v63, v33
	v_lshl_add_u64 v[62:63], v[68:69], 0, v[62:63]
	global_store_short v[62:63], v58, off offset:96
	v_mul_u32_u24_e32 v58, 5, v76
	v_cvt_pk_bf16_f32 v62, v59, s0
	v_lshlrev_b32_e32 v58, 1, v58
	v_mov_b32_e32 v59, v33
	global_store_short v[68:69], v32, off offset:96
	v_lshlrev_b32_e32 v32, 2, v76
	v_lshl_add_u64 v[58:59], v[68:69], 0, v[58:59]
	global_store_short v[58:59], v62, off offset:96
	v_lshl_add_u64 v[58:59], v[68:69], 0, v[32:33]
	v_mul_u32_u24_e32 v32, 6, v76
	v_cvt_pk_bf16_f32 v62, v64, s0
	v_lshlrev_b32_e32 v32, 1, v32
	global_store_short v[58:59], v62, off offset:96
	v_lshl_add_u64 v[58:59], v[68:69], 0, v[32:33]
	v_mul_u32_u24_e32 v32, 3, v76
	v_cvt_pk_bf16_f32 v60, v60, s0
	v_lshlrev_b32_e32 v32, 1, v32
	global_store_short v[58:59], v60, off offset:96
	v_lshl_add_u64 v[58:59], v[68:69], 0, v[32:33]
	v_mul_u32_u24_e32 v32, 7, v76
	v_cvt_pk_bf16_f32 v60, v65, s0
	v_lshlrev_b32_e32 v32, 1, v32
	global_store_short v[58:59], v60, off offset:96
	v_cvt_pk_bf16_f32 v60, v61, s0
	v_lshl_add_u64 v[58:59], v[68:69], 0, v[32:33]
	global_store_short v[58:59], v60, off offset:96

; __device__ __forceinline__ float ss_rinv(u64 v) { return __builtin_amdgcn_rsqf((float)v * SS_INV + 1e-6f); }
; __device__ __forceinline__ unsigned cvtpk(float lo, float hi) { f32x2 v = {lo, hi}; bf16x2_t b = __builtin_convertvector(v, bf16x2_t); return __builtin_bit_cast(unsigned, b); }
;     __device__ __forceinline__ void operator()(const f32x4 (&acc)[2][2][4][2], const pg8::Unit& u, int wr, int wc, int fr, int fq) const {
;     ...
;                 const int lrow = u.pm * 256 + ai * 128 + wr * 64 + m * 16 + fr, grow = row_base + lrow;
;                 if (grow >= MREAL) continue;
;                 const float ri = ss_rinv(rowss[grow]);
; #pragma unroll
;                 for (int bj = 0; bj < 2; ++bj) {
;                     const int col0 = u.pn * 256 + bj * 128 + wc * 32 + 8 * fq;
;                     f32x4 v0 = acc[ai][bj][m][0] * ri, v1 = acc[ai][bj][m][1] * ri;
;                     if (MODE == 1) {
; #pragma unroll
;                         for (int i = 0; i < 4; ++i) { const float a = fmaxf(v0[i], 0.f), b = fmaxf(v1[i], 0.f); v0[i] = a * a; v1[i] = b * b; }
;                         u32x4 w; w.x = cvtpk(v0[0], v0[1]); w.y = cvtpk(v0[2], v0[3]); w.z = cvtpk(v1[0], v1[1]); w.w = cvtpk(v1[2], v1[3]);
;                         *(u32x4*)(O + (size_t)lrow * DFF + col0) = w;
;                     } else {
;                         if (col0 < 1280) {
;                             u32x4 w; w.x = cvtpk(v0[0], v0[1]); w.y = cvtpk(v0[2], v0[3]); w.z = cvtpk(v1[0], v1[1]); w.w = cvtpk(v1[2], v1[3]);
;                             *(u32x4*)(O + (size_t)grow * 1280 + col0) = w;
;                         } else {
;                             int s, p, L; row_decode(grow, s, p, L);
;                             const int LS = seq_LS(s);
;                             bf16_t* dst = VT + seq_off_ch(s) / 4 + (size_t)(col0 - 1280) * LS + XPAD + p;
; #pragma unroll
;                             for (int i = 0; i < 4; ++i) { dst[(size_t)i * LS] = (bf16_t)(cvtpk(v0[i], 0.f) & 0xffffu); dst[(size_t)(4 + i) * LS] = (bf16_t)(cvtpk(v1[i], 0.f) & 0xffffu); }
.LBB0_527:
	s_or_b64 exec, exec, s[28:29]
	v_add_u32_e32 v51, 0x90, v144
	v_cmp_gt_i32_e32 vcc, s54, v51
	s_and_saveexec_b64 s[28:29], vcc
	s_cbranch_execz .LBB0_544
	v_mov_b64_e32 v[52:53], v[182:183]
	s_mov_b32 s2, 0x8000
	v_cmp_gt_i32_e32 vcc, s2, v51
	s_mov_b32 s2, 0x18000
	v_cmp_gt_u32_e64 s[2:3], s2, v51
	s_movk_i32 s6, 0x4ff
	v_ashrrev_i32_e32 v56, 13, v51
	v_cmp_lt_i32_e64 s[6:7], s6, v142
	v_ffbh_u32_e32 v32, v53
	v_min_u32_e32 v32, 32, v32
	v_lshlrev_b64 v[52:53], v32, v[52:53]
	v_min_u32_e32 v50, 1, v52
	v_or_b32_e32 v50, v53, v50
	v_cvt_f32_u32_e32 v50, v50
	v_sub_u32_e32 v32, 32, v32
	v_add_u32_e32 v52, 0xffff8090, v144
	v_lshrrev_b32_e32 v52, 12, v52
	v_ldexp_f32 v32, v50, v32
	v_fmamk_f32 v32, v32, 0x30800000, v203
	v_rsq_f32_e32 v50, v32
	v_add_u32_e32 v32, 0xfffe8090, v144
	v_and_b32_e32 v53, 0xfdf, v51
	v_lshrrev_b32_e32 v32, 4, v32
	v_add_u32_e32 v52, 4, v52
	v_add_u32_e32 v54, 16, v53
	v_and_b32_e32 v53, 0x1fdf, v51
	v_add_u32_e32 v55, 16, v53
	v_pk_mul_f32 v[48:49], v[48:49], v[50:51] op_sel_hi:[1,0]
	v_pk_mul_f32 v[46:47], v[46:47], v[50:51] op_sel_hi:[1,0]
	v_pk_mul_f32 v[44:45], v[44:45], v[50:51] op_sel_hi:[1,0]
	v_pk_mul_f32 v[42:43], v[42:43], v[50:51] op_sel_hi:[1,0]
	v_cndmask_b32_e64 v57, v32, v52, s[2:3]
	s_and_saveexec_b64 s[8:9], s[6:7]
	s_xor_b64 s[30:31], exec, s[8:9]
	s_cbranch_execz .LBB0_534
	v_cndmask_b32_e32 v32, v57, v56, vcc
	v_cmp_gt_i32_e64 s[6:7], 4, v32
	v_cmp_lt_i32_e64 s[8:9], 3, v32
	s_and_saveexec_b64 s[50:51], s[8:9]
	s_xor_b64 s[8:9], exec, s[50:51]
	v_add_u32_e32 v32, -4, v32
	s_mov_b32 s21, 0x410000
	v_mov_b64_e32 v[52:53], 0x2040000
	v_mad_u64_u32 v[52:53], s[50:51], v32, s21, v[52:53]
	s_andn2_saveexec_b64 s[8:9], s[8:9]
	s_mov_b32 s21, 0x810000
	v_mad_i64_i32 v[52:53], s[50:51], v32, s21, 0
	s_or_b64 exec, exec, s[8:9]
	v_mov_b32_e32 v58, 0x1040
	v_mov_b32_e32 v59, 0x2040
	v_lshrrev_b64 v[52:53], 1, v[52:53]
	v_cndmask_b32_e64 v32, v162, v54, s[2:3]
	v_cndmask_b32_e64 v60, v58, v59, s[6:7]
	v_and_b32_e32 v52, -2, v52
	v_add_u32_e32 v58, 0xfffffb00, v142
	v_cndmask_b32_e32 v32, v32, v55, vcc
	v_lshl_add_u64 v[52:53], s[14:15], 0, v[52:53]
	v_mad_u64_u32 v[58:59], s[6:7], v60, v58, 0
	v_lshl_add_u64 v[52:53], v[58:59], 1, v[52:53]
	v_lshlrev_b32_e32 v32, 1, v32
	v_lshl_add_u64 v[52:53], v[52:53], 0, v[32:33]
	v_lshlrev_b32_e32 v58, 3, v60
	v_mov_b32_e32 v59, v33
	v_cvt_pk_bf16_f32 v42, v42, s0
	v_lshl_add_u64 v[58:59], v[52:53], 0, v[58:59]
	v_cvt_pk_bf16_f32 v32, v46, s0
	global_store_short v[58:59], v42, off offset:96
	v_cvt_pk_bf16_f32 v42, v47, s0
	v_lshlrev_b32_e32 v46, 1, v60
	v_mov_b32_e32 v47, v33
	v_lshl_add_u64 v[46:47], v[52:53], 0, v[46:47]
	global_store_short v[46:47], v42, off offset:96
	v_mul_u32_u24_e32 v42, 5, v60
	v_cvt_pk_bf16_f32 v46, v43, s0
	v_lshlrev_b32_e32 v42, 1, v42
	v_mov_b32_e32 v43, v33
	global_store_short v[52:53], v32, off offset:96
	v_lshlrev_b32_e32 v32, 2, v60
	v_lshl_add_u64 v[42:43], v[52:53], 0, v[42:43]
	global_store_short v[42:43], v46, off offset:96
	v_lshl_add_u64 v[42:43], v[52:53], 0, v[32:33]
	v_mul_u32_u24_e32 v32, 6, v60
	v_cvt_pk_bf16_f32 v46, v48, s0
	v_lshlrev_b32_e32 v32, 1, v32
	global_store_short v[42:43], v46, off offset:96
	v_lshl_add_u64 v[42:43], v[52:53], 0, v[32:33]
	v_mul_u32_u24_e32 v32, 3, v60
	v_cvt_pk_bf16_f32 v44, v44, s0
	v_lshlrev_b32_e32 v32, 1, v32
	global_store_short v[42:43], v44, off offset:96
	v_lshl_add_u64 v[42:43], v[52:53], 0, v[32:33]
	v_mul_u32_u24_e32 v32, 7, v60
	v_cvt_pk_bf16_f32 v44, v49, s0
	v_lshlrev_b32_e32 v32, 1, v32
	global_store_short v[42:43], v44, off offset:96
	v_cvt_pk_bf16_f32 v44, v45, s0
	v_lshl_add_u64 v[42:43], v[52:53], 0, v[32:33]
	global_store_short v[42:43], v44, off offset:96

; __device__ __forceinline__ float ss_rinv(u64 v) { return __builtin_amdgcn_rsqf((float)v * SS_INV + 1e-6f); }
; __device__ __forceinline__ unsigned cvtpk(float lo, float hi) { f32x2 v = {lo, hi}; bf16x2_t b = __builtin_convertvector(v, bf16x2_t); return __builtin_bit_cast(unsigned, b); }
;     __device__ __forceinline__ void operator()(const f32x4 (&acc)[2][2][4][2], const pg8::Unit& u, int wr, int wc, int fr, int fq) const {
;     ...
;                 const int lrow = u.pm * 256 + ai * 128 + wr * 64 + m * 16 + fr, grow = row_base + lrow;
;                 if (grow >= MREAL) continue;
;                 const float ri = ss_rinv(rowss[grow]);
; #pragma unroll
;                 for (int bj = 0; bj < 2; ++bj) {
;                     const int col0 = u.pn * 256 + bj * 128 + wc * 32 + 8 * fq;
;                     f32x4 v0 = acc[ai][bj][m][0] * ri, v1 = acc[ai][bj][m][1] * ri;
;                     if (MODE == 1) {
; #pragma unroll
;                         for (int i = 0; i < 4; ++i) { const float a = fmaxf(v0[i], 0.f), b = fmaxf(v1[i], 0.f); v0[i] = a * a; v1[i] = b * b; }
;                         u32x4 w; w.x = cvtpk(v0[0], v0[1]); w.y = cvtpk(v0[2], v0[3]); w.z = cvtpk(v1[0], v1[1]); w.w = cvtpk(v1[2], v1[3]);
;                         *(u32x4*)(O + (size_t)lrow * DFF + col0) = w;
;                     } else {
;                         if (col0 < 1280) {
;                             u32x4 w; w.x = cvtpk(v0[0], v0[1]); w.y = cvtpk(v0[2], v0[3]); w.z = cvtpk(v1[0], v1[1]); w.w = cvtpk(v1[2], v1[3]);
;                             *(u32x4*)(O + (size_t)grow * 1280 + col0) = w;
;                         } else {
;                             int s, p, L; row_decode(grow, s, p, L);
;                             const int LS = seq_LS(s);
;                             bf16_t* dst = VT + seq_off_ch(s) / 4 + (size_t)(col0 - 1280) * LS + XPAD + p;
; #pragma unroll
;                             for (int i = 0; i < 4; ++i) { dst[(size_t)i * LS] = (bf16_t)(cvtpk(v0[i], 0.f) & 0xffffu); dst[(size_t)(4 + i) * LS] = (bf16_t)(cvtpk(v1[i], 0.f) & 0xffffu); }
.LBB0_544:
	s_or_b64 exec, exec, s[28:29]
	v_add_u32_e32 v35, 0xa0, v144
	v_cmp_gt_i32_e32 vcc, s54, v35
	s_and_saveexec_b64 s[28:29], vcc
	s_cbranch_execz .LBB0_561
	v_mov_b64_e32 v[36:37], v[184:185]
	s_mov_b32 s2, 0x8000
	s_movk_i32 s6, 0xfef
	v_cmp_gt_i32_e32 vcc, s2, v35
	s_mov_b32 s2, 0x18000
	v_and_or_b32 v38, v35, s6, 16
	s_movk_i32 s6, 0x1fef
	v_cmp_gt_u32_e64 s[2:3], s2, v35
	v_and_or_b32 v39, v35, s6, 16
	s_movk_i32 s6, 0x4ff
	v_ashrrev_i32_e32 v40, 13, v35
	v_cmp_lt_i32_e64 s[6:7], s6, v142
	v_ffbh_u32_e32 v32, v37
	v_min_u32_e32 v32, 32, v32
	v_lshlrev_b64 v[36:37], v32, v[36:37]
	v_min_u32_e32 v34, 1, v36
	v_or_b32_e32 v34, v37, v34
	v_cvt_f32_u32_e32 v34, v34
	v_sub_u32_e32 v32, 32, v32
	v_add_u32_e32 v36, 0xffff80a0, v144
	v_lshrrev_b32_e32 v36, 12, v36
	v_ldexp_f32 v32, v34, v32
	v_fmamk_f32 v32, v32, 0x30800000, v203
	v_rsq_f32_e32 v34, v32
	v_add_u32_e32 v32, 0xfffe80a0, v144
	v_lshrrev_b32_e32 v32, 4, v32
	v_add_u32_e32 v36, 4, v36
	v_pk_mul_f32 v[30:31], v[30:31], v[34:35] op_sel_hi:[1,0]
	v_pk_mul_f32 v[28:29], v[28:29], v[34:35] op_sel_hi:[1,0]
	v_pk_mul_f32 v[26:27], v[26:27], v[34:35] op_sel_hi:[1,0]
	v_pk_mul_f32 v[24:25], v[24:25], v[34:35] op_sel_hi:[1,0]
	v_cndmask_b32_e64 v41, v32, v36, s[2:3]
	s_and_saveexec_b64 s[8:9], s[6:7]
	s_xor_b64 s[30:31], exec, s[8:9]
	s_cbranch_execz .LBB0_551
	v_cndmask_b32_e32 v32, v41, v40, vcc
	v_cmp_gt_i32_e64 s[6:7], 4, v32
	v_cmp_lt_i32_e64 s[8:9], 3, v32
	s_and_saveexec_b64 s[50:51], s[8:9]
	s_xor_b64 s[8:9], exec, s[50:51]
	v_add_u32_e32 v32, -4, v32
	s_mov_b32 s21, 0x410000
	v_mov_b64_e32 v[36:37], 0x2040000
	v_mad_u64_u32 v[36:37], s[50:51], v32, s21, v[36:37]
	s_andn2_saveexec_b64 s[8:9], s[8:9]
	s_mov_b32 s21, 0x810000
	v_mad_i64_i32 v[36:37], s[50:51], v32, s21, 0
	s_or_b64 exec, exec, s[8:9]
	v_mov_b32_e32 v42, 0x1040
	v_mov_b32_e32 v43, 0x2040
	v_lshrrev_b64 v[36:37], 1, v[36:37]
	v_cndmask_b32_e64 v32, v162, v38, s[2:3]
	v_cndmask_b32_e64 v44, v42, v43, s[6:7]
	v_and_b32_e32 v36, -2, v36
	v_add_u32_e32 v42, 0xfffffb00, v142
	v_cndmask_b32_e32 v32, v32, v39, vcc
	v_lshl_add_u64 v[36:37], s[14:15], 0, v[36:37]
	v_mad_u64_u32 v[42:43], s[6:7], v44, v42, 0
	v_lshl_add_u64 v[36:37], v[42:43], 1, v[36:37]
	v_lshlrev_b32_e32 v32, 1, v32
	v_lshl_add_u64 v[36:37], v[36:37], 0, v[32:33]
	v_lshlrev_b32_e32 v42, 3, v44
	v_mov_b32_e32 v43, v33
	v_cvt_pk_bf16_f32 v28, v28, s0
	v_cvt_pk_bf16_f32 v24, v24, s0
	v_lshl_add_u64 v[42:43], v[36:37], 0, v[42:43]
	global_store_short v[36:37], v28, off offset:96
	global_store_short v[42:43], v24, off offset:96
	v_cvt_pk_bf16_f32 v24, v29, s0
	v_lshlrev_b32_e32 v28, 1, v44
	v_mov_b32_e32 v29, v33
	v_lshl_add_u64 v[28:29], v[36:37], 0, v[28:29]
	global_store_short v[28:29], v24, off offset:96
	v_mul_u32_u24_e32 v24, 5, v44
	v_cvt_pk_bf16_f32 v28, v25, s0
	v_lshlrev_b32_e32 v24, 1, v24
	v_mov_b32_e32 v25, v33
	v_lshlrev_b32_e32 v32, 2, v44
	v_lshl_add_u64 v[24:25], v[36:37], 0, v[24:25]
	global_store_short v[24:25], v28, off offset:96
	v_cvt_pk_bf16_f32 v28, v30, s0
	v_lshl_add_u64 v[24:25], v[36:37], 0, v[32:33]
	global_store_short v[24:25], v28, off offset:96
	v_mul_u32_u24_e32 v24, 6, v44
	v_lshlrev_b32_e32 v32, 1, v24
	v_cvt_pk_bf16_f32 v26, v26, s0
	v_lshl_add_u64 v[24:25], v[36:37], 0, v[32:33]
	global_store_short v[24:25], v26, off offset:96
	v_mul_u32_u24_e32 v24, 3, v44
	v_lshlrev_b32_e32 v32, 1, v24
	v_cvt_pk_bf16_f32 v26, v31, s0
	v_lshl_add_u64 v[24:25], v[36:37], 0, v[32:33]
	global_store_short v[24:25], v26, off offset:96
	v_mul_u32_u24_e32 v24, 7, v44
	v_lshlrev_b32_e32 v32, 1, v24
	v_cvt_pk_bf16_f32 v26, v27, s0
	v_lshl_add_u64 v[24:25], v[36:37], 0, v[32:33]
	global_store_short v[24:25], v26, off offset:96

; __device__ __forceinline__ float ss_rinv(u64 v) { return __builtin_amdgcn_rsqf((float)v * SS_INV + 1e-6f); }
; __device__ __forceinline__ unsigned cvtpk(float lo, float hi) { f32x2 v = {lo, hi}; bf16x2_t b = __builtin_convertvector(v, bf16x2_t); return __builtin_bit_cast(unsigned, b); }
;     __device__ __forceinline__ void operator()(const f32x4 (&acc)[2][2][4][2], const pg8::Unit& u, int wr, int wc, int fr, int fq) const {
;     ...
;                 const int lrow = u.pm * 256 + ai * 128 + wr * 64 + m * 16 + fr, grow = row_base + lrow;
;                 if (grow >= MREAL) continue;
;                 const float ri = ss_rinv(rowss[grow]);
; #pragma unroll
;                 for (int bj = 0; bj < 2; ++bj) {
;                     const int col0 = u.pn * 256 + bj * 128 + wc * 32 + 8 * fq;
;                     f32x4 v0 = acc[ai][bj][m][0] * ri, v1 = acc[ai][bj][m][1] * ri;
;                     if (MODE == 1) {
; #pragma unroll
;                         for (int i = 0; i < 4; ++i) { const float a = fmaxf(v0[i], 0.f), b = fmaxf(v1[i], 0.f); v0[i] = a * a; v1[i] = b * b; }
;                         u32x4 w; w.x = cvtpk(v0[0], v0[1]); w.y = cvtpk(v0[2], v0[3]); w.z = cvtpk(v1[0], v1[1]); w.w = cvtpk(v1[2], v1[3]);
;                         *(u32x4*)(O + (size_t)lrow * DFF + col0) = w;
;                     } else {
;                         if (col0 < 1280) {
;                             u32x4 w; w.x = cvtpk(v0[0], v0[1]); w.y = cvtpk(v0[2], v0[3]); w.z = cvtpk(v1[0], v1[1]); w.w = cvtpk(v1[2], v1[3]);
;                             *(u32x4*)(O + (size_t)grow * 1280 + col0) = w;
;                         } else {
;                             int s, p, L; row_decode(grow, s, p, L);
;                             const int LS = seq_LS(s);
;                             bf16_t* dst = VT + seq_off_ch(s) / 4 + (size_t)(col0 - 1280) * LS + XPAD + p;
; #pragma unroll
;                             for (int i = 0; i < 4; ++i) { dst[(size_t)i * LS] = (bf16_t)(cvtpk(v0[i], 0.f) & 0xffffu); dst[(size_t)(4 + i) * LS] = (bf16_t)(cvtpk(v1[i], 0.f) & 0xffffu); }
.LBB0_561:
	s_or_b64 exec, exec, s[28:29]
	v_add_u32_e32 v17, 0xb0, v144
	v_cmp_gt_i32_e32 vcc, s54, v17
	s_and_saveexec_b64 s[28:29], vcc
	s_cbranch_execz .LBB0_578
	v_mov_b64_e32 v[18:19], v[186:187]
	s_mov_b32 s2, 0x8000
	v_cmp_gt_i32_e32 vcc, s2, v17
	s_mov_b32 s2, 0x18000
	v_cmp_gt_u32_e64 s[2:3], s2, v17
	v_and_b32_e32 v20, 0xfff, v17
	v_and_b32_e32 v21, 0x1fff, v17
	s_movk_i32 s6, 0x4ff
	v_add_u32_e32 v20, 16, v20
	v_ashrrev_i32_e32 v22, 13, v17
	v_add_u32_e32 v21, 16, v21
	v_cmp_lt_i32_e64 s[6:7], s6, v142
	v_ffbh_u32_e32 v16, v19
	v_min_u32_e32 v16, 32, v16
	v_lshlrev_b64 v[18:19], v16, v[18:19]
	v_min_u32_e32 v18, 1, v18
	v_or_b32_e32 v18, v19, v18
	v_cvt_f32_u32_e32 v18, v18
	v_sub_u32_e32 v16, 32, v16
	v_add_u32_e32 v19, 0xffff80b0, v144
	v_lshrrev_b32_e32 v19, 12, v19
	v_ldexp_f32 v16, v18, v16
	v_fmamk_f32 v16, v16, 0x30800000, v203
	v_rsq_f32_e32 v16, v16
	v_add_u32_e32 v18, 0xfffe80b0, v144
	v_lshrrev_b32_e32 v18, 4, v18
	v_add_u32_e32 v19, 4, v19
	v_pk_mul_f32 v[14:15], v[14:15], v[16:17] op_sel_hi:[1,0]
	v_pk_mul_f32 v[12:13], v[12:13], v[16:17] op_sel_hi:[1,0]
	v_pk_mul_f32 v[10:11], v[10:11], v[16:17] op_sel_hi:[1,0]
	v_pk_mul_f32 v[8:9], v[8:9], v[16:17] op_sel_hi:[1,0]
	v_cndmask_b32_e64 v23, v18, v19, s[2:3]
	s_and_saveexec_b64 s[8:9], s[6:7]
	s_xor_b64 s[30:31], exec, s[8:9]
	s_cbranch_execz .LBB0_568
	v_cndmask_b32_e32 v24, v23, v22, vcc
	v_cmp_gt_i32_e64 s[6:7], 4, v24
	v_cmp_lt_i32_e64 s[8:9], 3, v24
	s_and_saveexec_b64 s[50:51], s[8:9]
	s_xor_b64 s[8:9], exec, s[50:51]
	v_add_u32_e32 v18, -4, v24
	s_mov_b32 s21, 0x410000
	v_mov_b64_e32 v[24:25], 0x2040000
	v_mad_u64_u32 v[18:19], s[50:51], v18, s21, v[24:25]
	s_andn2_saveexec_b64 s[8:9], s[8:9]
	s_mov_b32 s21, 0x810000
	v_mad_i64_i32 v[18:19], s[50:51], v24, s21, 0
	s_or_b64 exec, exec, s[8:9]
	v_cndmask_b32_e64 v24, v162, v20, s[2:3]
	v_cndmask_b32_e32 v26, v24, v21, vcc
	v_mov_b32_e32 v24, 0x1040
	v_mov_b32_e32 v25, 0x2040
	v_lshrrev_b64 v[18:19], 1, v[18:19]
	v_cndmask_b32_e64 v27, v24, v25, s[6:7]
	v_and_b32_e32 v18, -2, v18
	v_add_u32_e32 v24, 0xfffffb00, v142
	v_lshl_add_u64 v[18:19], s[14:15], 0, v[18:19]
	v_mad_u64_u32 v[24:25], s[6:7], v27, v24, 0
	v_lshl_add_u64 v[18:19], v[24:25], 1, v[18:19]
	v_lshlrev_b32_e32 v32, 1, v26
	v_lshl_add_u64 v[18:19], v[18:19], 0, v[32:33]
	v_lshlrev_b32_e32 v24, 3, v27
	v_mov_b32_e32 v25, v33
	v_cvt_pk_bf16_f32 v12, v12, s0
	v_cvt_pk_bf16_f32 v8, v8, s0
	v_lshl_add_u64 v[24:25], v[18:19], 0, v[24:25]
	global_store_short v[18:19], v12, off offset:96
	global_store_short v[24:25], v8, off offset:96
	v_cvt_pk_bf16_f32 v8, v13, s0
	v_lshlrev_b32_e32 v12, 1, v27
	v_mov_b32_e32 v13, v33
	v_lshl_add_u64 v[12:13], v[18:19], 0, v[12:13]
	global_store_short v[12:13], v8, off offset:96
	v_mul_u32_u24_e32 v8, 5, v27
	v_cvt_pk_bf16_f32 v12, v9, s0
	v_lshlrev_b32_e32 v8, 1, v8
	v_mov_b32_e32 v9, v33
	v_lshlrev_b32_e32 v32, 2, v27
	v_lshl_add_u64 v[8:9], v[18:19], 0, v[8:9]
	global_store_short v[8:9], v12, off offset:96
	v_cvt_pk_bf16_f32 v12, v14, s0
	v_lshl_add_u64 v[8:9], v[18:19], 0, v[32:33]
	global_store_short v[8:9], v12, off offset:96
	v_mul_u32_u24_e32 v8, 6, v27
	v_lshlrev_b32_e32 v32, 1, v8
	v_cvt_pk_bf16_f32 v10, v10, s0
	v_lshl_add_u64 v[8:9], v[18:19], 0, v[32:33]
	global_store_short v[8:9], v10, off offset:96
	v_mul_u32_u24_e32 v8, 3, v27
	v_lshlrev_b32_e32 v32, 1, v8
	v_cvt_pk_bf16_f32 v10, v15, s0
	v_lshl_add_u64 v[8:9], v[18:19], 0, v[32:33]
	global_store_short v[8:9], v10, off offset:96
	v_mul_u32_u24_e32 v8, 7, v27
	v_lshlrev_b32_e32 v32, 1, v8
	v_cvt_pk_bf16_f32 v10, v11, s0
	v_lshl_add_u64 v[8:9], v[18:19], 0, v[32:33]
	global_store_short v[8:9], v10, off offset:96
